# in-proj and gate/up epilogues: per-lane row sum-of-squares partials cached in 8 spare VGPRs and reused while the workgroup stays on the same row tile (skips 8 loads and the vmcnt(0) before the epilogu
# speedup vs baseline: 1.0107x; 1.0035x over previous
.LBB0_249:
	s_waitcnt lgkmcnt(0)
	s_mov_b32 s99, -1
	s_mov_b64 s[6:7], s[44:45]
	s_mul_hi_u32 s1, s84, 0x1a00000
	s_mov_b32 s4, 4
	s_mov_b32 s8, 5
	s_mov_b32 s5, -1
	v_writelane_b32 v255, s1, 42
	s_mul_i32 s1, s84, 0x1a00000
	v_mbcnt_lo_u32_b32 v0, s5, 0
	v_mbcnt_hi_u32_b32 v0, s5, v0
	v_readlane_b32 s10, v255, 7
	v_or_b32_e32 v8, s33, v0
	v_readlane_b32 s11, v255, 8
	s_and_b64 vcc, exec, s[10:11]
	v_readfirstlane_b32 s26, v8
	s_cbranch_vccz .LBB0_471
	v_lshlrev_b32_e32 v0, 4, v8
	v_add_u32_e32 v1, 0x2000, v0
	v_ashrrev_i32_e32 v2, 31, v1
	v_lshrrev_b32_e32 v2, 22, v2
	v_add_u32_e32 v2, v1, v2
	s_add_u32 s48, s6, 0x6900000
	v_ashrrev_i32_e32 v9, 10, v2
	s_addc_u32 s49, s7, 0
	v_mul_i32_i24_e32 v2, 0x400, v9
	s_add_u32 s5, s6, s1
	s_mul_hi_u32 s9, s84, 0x1a00000
	v_sub_u32_e32 v1, v1, v2
	s_addc_u32 s9, s7, s9
	v_lshrrev_b32_e32 v2, 4, v1
	s_add_u32 s50, s5, 0x100000
	v_bitop3_b32 v1, v2, v1, 32 bitop3:0x6c
	s_addc_u32 s51, s9, 0
	s_ashr_i32 s5, s4, 31
	v_ashrrev_i32_e32 v2, 31, v1
	s_lshl_b64 s[4:5], s[4:5], 3
	v_readlane_b32 s10, v255, 5
	v_lshrrev_b32_e32 v2, 26, v2
	v_readlane_b32 s11, v255, 6
	s_add_u32 s4, s10, s4
	v_add_u32_e32 v2, v1, v2
	v_lshlrev_b32_e32 v3, 3, v9
	s_addc_u32 s5, s11, s5
	s_ashr_i32 s9, s8, 31
	v_ashrrev_i32_e32 v10, 6, v2
	v_and_b32_e32 v3, -16, v3
	s_lshl_b64 s[8:9], s[8:9], 3
	v_add_u32_e32 v3, v10, v3
	s_add_u32 s10, s10, s8
	v_and_b32_e32 v4, 3, v10
	s_mov_b32 s8, 0x1fffe0
	v_lshrrev_b32_e32 v5, 2, v3
	v_lshlrev_b32_e32 v6, 1, v3
	v_and_b32_e32 v2, 0xc0, v2
	v_and_or_b32 v4, v3, s8, v4
	v_and_b32_e32 v5, 4, v5
	v_and_b32_e32 v6, 24, v6
	v_sub_u32_e32 v1, v1, v2
	v_or3_b32 v4, v4, v5, v6
	v_lshlrev_b32_e32 v5, 5, v9
	v_ashrrev_i16_sdwa v1, v237, sext(v1) dst_sel:DWORD dst_unused:UNUSED_PAD src0_sel:DWORD src1_sel:BYTE_0
	v_and_b32_e32 v5, 32, v5
	v_bfe_i32 v11, v1, 0, 16
	v_add_lshl_u32 v1, v5, v11, 1
	v_lshl_add_u32 v152, v4, 11, v1
	v_lshl_add_u32 v154, v3, 11, v1
	v_bfe_i32 v1, v8, 27, 1
	v_lshrrev_b32_e32 v1, 22, v1
	v_add_u32_e32 v1, v0, v1
	v_and_b32_e32 v1, 0xfffffc00, v1
	v_sub_u32_e32 v0, v0, v1
	v_lshrrev_b32_e32 v1, 4, v0
	v_ashrrev_i32_e32 v2, 31, v8
	v_bitop3_b32 v0, v1, v0, 32 bitop3:0x6c
	v_lshrrev_b32_e32 v2, 26, v2
	v_ashrrev_i32_e32 v1, 31, v0
	v_add_u32_e32 v2, v8, v2
	v_lshrrev_b32_e32 v1, 26, v1
	v_ashrrev_i32_e32 v13, 6, v2
	v_add_u32_e32 v1, v0, v1
	v_lshlrev_b32_e32 v2, 3, v13
	v_ashrrev_i32_e32 v12, 6, v1
	v_and_b32_e32 v2, -16, v2
	v_add_u32_e32 v2, v12, v2
	v_and_b32_e32 v3, 3, v12
	v_lshrrev_b32_e32 v4, 2, v2
	v_lshlrev_b32_e32 v5, 1, v2
	v_and_b32_e32 v1, 0xc0, v1
	s_addc_u32 s11, s11, s9
	s_ashr_i32 s28, s26, 6
	v_and_or_b32 v3, v2, s8, v3
	v_and_b32_e32 v4, 4, v4
	v_and_b32_e32 v5, 24, v5
	v_sub_u32_e32 v0, v0, v1
	s_ashr_i32 s27, s26, 8
	s_lshl_b32 s54, s28, 10
	v_or3_b32 v3, v3, v4, v5
	v_lshlrev_b32_e32 v4, 5, v13
	v_ashrrev_i16_sdwa v0, v237, sext(v0) dst_sel:DWORD dst_unused:UNUSED_PAD src0_sel:DWORD src1_sel:BYTE_0
	v_readlane_b32 s8, v255, 23
	v_and_b32_e32 v4, 32, v4
	v_bfe_i32 v14, v0, 0, 16
	v_readlane_b32 s9, v255, 24
	s_add_u32 s8, s50, s8
	v_add_lshl_u32 v0, v4, v14, 1
	s_addc_u32 s9, s51, s9
	s_add_i32 s55, s54, 0
	v_lshl_add_u32 v192, v3, 11, v0
	s_add_i32 m0, s55, 0x10000
	v_lshl_add_u32 v156, v2, 11, v0
	global_load_lds_dwordx4 v192, s[8:9]
	s_add_i32 m0, s55, 0x12000
	s_add_u32 s12, s8, 0x40000
	global_load_lds_dwordx4 v152, s[8:9]
	s_addc_u32 s13, s9, 0
	s_add_i32 m0, s55, 0x14000
	v_mov_b32_e32 v153, v193
	global_load_lds_dwordx4 v192, s[12:13]
	s_add_i32 m0, s55, 0x16000
	v_mov_b32_e32 v157, v193
	global_load_lds_dwordx4 v152, s[12:13]
	v_readlane_b32 s12, v255, 36
	v_readlane_b32 s13, v255, 37
	s_add_u32 s38, s48, s12
	s_addc_u32 s39, s49, s13
	s_add_i32 s60, s55, 0x2000
	s_mov_b32 m0, s55
	s_add_u32 s12, s38, 0x40000
	global_load_lds_dwordx4 v156, s[38:39]
	s_mov_b32 m0, s60
	s_addc_u32 s13, s39, 0
	s_add_i32 s61, s55, 0x4000
	global_load_lds_dwordx4 v154, s[38:39]
	s_mov_b32 m0, s61
	s_add_i32 s82, s55, 0x6000
	global_load_lds_dwordx4 v156, s[12:13]
	s_mov_b32 m0, s82
	v_mov_b32_e32 v155, v193
	global_load_lds_dwordx4 v154, s[12:13]
	s_load_dwordx2 s[22:23], s[4:5], 0x0
	s_nop 0
	s_load_dwordx2 s[4:5], s[10:11], 0x0
	s_cmp_eq_u32 s27, 1
	v_lshl_add_u64 v[6:7], s[8:9], 0, v[192:193]
	v_lshl_add_u64 v[4:5], s[8:9], 0, v[152:153]
	v_lshl_add_u64 v[0:1], s[38:39], 0, v[156:157]
	s_cselect_b64 s[10:11], -1, 0
	s_cmp_lg_u32 s27, 1
	v_lshl_add_u64 v[2:3], s[38:39], 0, v[154:155]
	s_cbranch_scc1 .LBB0_252
	s_barrier

.LBB0_261:
	s_cmp_eq_u32 s46, s99
	s_cbranch_scc1 .Lp2_rr_hit
	v_lshl_add_u32 v178, s46, 8, v181
	v_ashrrev_i32_e32 v179, 31, v178
	v_lshlrev_b64 v[128:129], 6, v[178:179]
	v_or_b32_e32 v176, 16, v178
	v_lshl_add_u64 v[128:129], v[158:159], 0, v[128:129]
	v_ashrrev_i32_e32 v177, 31, v176
	global_load_dwordx4 v[202:205], v[128:129], off
	v_lshlrev_b64 v[128:129], 6, v[176:177]
	v_lshl_add_u64 v[128:129], v[158:159], 0, v[128:129]
	global_load_dwordx4 v[206:209], v[128:129], off
	v_or_b32_e32 v174, 32, v178
	v_ashrrev_i32_e32 v175, 31, v174
	v_lshlrev_b64 v[128:129], 6, v[174:175]
	v_or_b32_e32 v172, 48, v178
	v_lshl_add_u64 v[128:129], v[158:159], 0, v[128:129]
	v_ashrrev_i32_e32 v173, 31, v172
	global_load_dwordx4 v[148:151], v[128:129], off
	v_lshlrev_b64 v[128:129], 6, v[172:173]
	v_lshl_add_u64 v[128:129], v[158:159], 0, v[128:129]
	global_load_dwordx4 v[144:147], v[128:129], off
	v_add_u32_e32 v170, 0x80, v178
	v_ashrrev_i32_e32 v171, 31, v170
	v_lshlrev_b64 v[128:129], 6, v[170:171]
	v_add_u32_e32 v168, 0x90, v178
	v_lshl_add_u64 v[128:129], v[158:159], 0, v[128:129]
	v_ashrrev_i32_e32 v169, 31, v168
	global_load_dwordx4 v[140:143], v[128:129], off
	v_lshlrev_b64 v[128:129], 6, v[168:169]
	v_lshl_add_u64 v[128:129], v[158:159], 0, v[128:129]
	global_load_dwordx4 v[136:139], v[128:129], off
	v_add_u32_e32 v166, 0xa0, v178
	v_ashrrev_i32_e32 v167, 31, v166
	v_lshlrev_b64 v[128:129], 6, v[166:167]
	v_add_u32_e32 v164, 0xb0, v178
	v_lshl_add_u64 v[128:129], v[158:159], 0, v[128:129]
	v_ashrrev_i32_e32 v165, 31, v164
	global_load_dwordx4 v[132:135], v[128:129], off
	v_lshlrev_b64 v[128:129], 6, v[164:165]
	v_lshl_add_u64 v[128:129], v[158:159], 0, v[128:129]
	global_load_dwordx4 v[128:131], v[128:129], off
	v_and_b32_e32 v182, 64, v239
	v_xor_b32_e32 v180, 16, v239
	v_add_u32_e32 v182, 64, v182
	v_cmp_lt_i32_e32 vcc, v180, v182
	s_cmp_gt_i32 s86, 13
	s_waitcnt vmcnt(0)
	v_add_f32_e32 v247, v202, v203
	v_add_f32_e32 v248, v204, v205
	v_add_f32_e32 v230, v247, v248
	v_add_f32_e32 v249, v206, v207
	v_add_f32_e32 v250, v208, v209
	v_add_f32_e32 v231, v249, v250
	v_add_f32_e32 v247, v148, v149
	v_add_f32_e32 v248, v150, v151
	v_add_f32_e32 v232, v247, v248
	v_add_f32_e32 v249, v144, v145
	v_add_f32_e32 v250, v146, v147
	v_add_f32_e32 v233, v249, v250
	v_add_f32_e32 v247, v140, v141
	v_add_f32_e32 v248, v142, v143
	v_add_f32_e32 v234, v247, v248
	v_add_f32_e32 v249, v136, v137
	v_add_f32_e32 v250, v138, v139
	v_add_f32_e32 v235, v249, v250
	v_add_f32_e32 v247, v132, v133
	v_add_f32_e32 v248, v134, v135
	v_add_f32_e32 v242, v247, v248
	v_add_f32_e32 v249, v128, v129
	v_add_f32_e32 v250, v130, v131
	v_add_f32_e32 v243, v249, v250
	s_mov_b32 s99, s46
	s_branch .Lp2_rr_join
.Lp2_rr_hit:
	v_lshl_add_u32 v178, s46, 8, v181
	v_ashrrev_i32_e32 v179, 31, v178
	v_lshlrev_b64 v[128:129], 6, v[178:179]
	v_or_b32_e32 v176, 16, v178
	v_lshl_add_u64 v[128:129], v[158:159], 0, v[128:129]
	v_ashrrev_i32_e32 v177, 31, v176
	v_lshlrev_b64 v[128:129], 6, v[176:177]
	v_lshl_add_u64 v[128:129], v[158:159], 0, v[128:129]
	v_or_b32_e32 v174, 32, v178
	v_ashrrev_i32_e32 v175, 31, v174
	v_lshlrev_b64 v[128:129], 6, v[174:175]
	v_or_b32_e32 v172, 48, v178
	v_lshl_add_u64 v[128:129], v[158:159], 0, v[128:129]
	v_ashrrev_i32_e32 v173, 31, v172
	v_lshlrev_b64 v[128:129], 6, v[172:173]
	v_lshl_add_u64 v[128:129], v[158:159], 0, v[128:129]
	v_add_u32_e32 v170, 0x80, v178
	v_ashrrev_i32_e32 v171, 31, v170
	v_lshlrev_b64 v[128:129], 6, v[170:171]
	v_add_u32_e32 v168, 0x90, v178
	v_lshl_add_u64 v[128:129], v[158:159], 0, v[128:129]
	v_ashrrev_i32_e32 v169, 31, v168
	v_lshlrev_b64 v[128:129], 6, v[168:169]
	v_lshl_add_u64 v[128:129], v[158:159], 0, v[128:129]
	v_add_u32_e32 v166, 0xa0, v178
	v_ashrrev_i32_e32 v167, 31, v166
	v_lshlrev_b64 v[128:129], 6, v[166:167]
	v_add_u32_e32 v164, 0xb0, v178
	v_lshl_add_u64 v[128:129], v[158:159], 0, v[128:129]
	v_ashrrev_i32_e32 v165, 31, v164
	v_lshlrev_b64 v[128:129], 6, v[164:165]
	v_lshl_add_u64 v[128:129], v[158:159], 0, v[128:129]
	v_and_b32_e32 v182, 64, v239
	v_xor_b32_e32 v180, 16, v239
	v_add_u32_e32 v182, 64, v182
	v_cmp_lt_i32_e32 vcc, v180, v182
	s_cmp_gt_i32 s86, 13
	v_mov_b32_e32 v202, v230
	v_mov_b32_e32 v203, 0
	v_mov_b64_e32 v[204:205], 0
	v_mov_b32_e32 v206, v231
	v_mov_b32_e32 v207, 0
	v_mov_b64_e32 v[208:209], 0
	v_mov_b32_e32 v148, v232
	v_mov_b32_e32 v149, 0
	v_mov_b64_e32 v[150:151], 0
	v_mov_b32_e32 v144, v233
	v_mov_b32_e32 v145, 0
	v_mov_b64_e32 v[146:147], 0
	v_mov_b32_e32 v140, v234
	v_mov_b32_e32 v141, 0
	v_mov_b64_e32 v[142:143], 0
	v_mov_b32_e32 v136, v235
	v_mov_b32_e32 v137, 0
	v_mov_b64_e32 v[138:139], 0
	v_mov_b32_e32 v132, v242
	v_mov_b32_e32 v133, 0
	v_mov_b64_e32 v[134:135], 0
	v_mov_b32_e32 v128, v243
	v_mov_b32_e32 v129, 0
	v_mov_b64_e32 v[130:131], 0
.Lp2_rr_join:
	v_mov_b32_e32 v184, v203
	v_mov_b32_e32 v185, v204
	v_mov_b32_e32 v203, v205
	v_mov_b32_e32 v190, v207
	v_mov_b32_e32 v191, v208
	v_mov_b32_e32 v207, v209
	v_pk_add_f32 v[184:185], v[184:185], v[202:203]
	v_pk_add_f32 v[190:191], v[190:191], v[206:207]
	v_cndmask_b32_e32 v180, v239, v180, vcc
	v_mov_b32_e32 v202, v190
	v_mov_b32_e32 v203, v184
	v_mov_b32_e32 v184, v191
	v_lshlrev_b32_e32 v189, 2, v180
	v_pk_add_f32 v[184:185], v[202:203], v[184:185]
	ds_bpermute_b32 v191, v189, v185
	ds_bpermute_b32 v190, v189, v184
	v_xor_b32_e32 v180, 32, v239
	v_cmp_lt_i32_e32 vcc, v180, v182
	s_waitcnt lgkmcnt(0)
	v_pk_add_f32 v[184:185], v[184:185], v[190:191]
	v_cndmask_b32_e32 v180, v239, v180, vcc
	v_lshlrev_b32_e32 v188, 2, v180
	ds_bpermute_b32 v191, v188, v185
	ds_bpermute_b32 v190, v188, v184
	s_waitcnt lgkmcnt(0)
	v_pk_add_f32 v[190:191], v[184:185], v[190:191]
	v_mov_b64_e32 v[184:185], s[80:81]
	v_pk_fma_f32 v[190:191], v[190:191], s[78:79], v[184:185] op_sel_hi:[1,0,0]
	s_nop 0
	v_mul_f32_e32 v180, 0x4b800000, v191
	v_cmp_gt_f32_e64 s[8:9], s66, v191
	v_cmp_gt_f32_e32 vcc, s66, v190
	s_nop 0
	v_cndmask_b32_e64 v180, v191, v180, s[8:9]
	v_rsq_f32_e32 v180, v180
	v_mov_b32_e32 v191, v150
	v_mov_b32_e32 v150, v145
	v_mov_b32_e32 v145, v147
	v_mul_f32_e32 v182, 0x45800000, v180
	v_cndmask_b32_e64 v182, v180, v182, s[8:9]
	v_mul_f32_e32 v180, 0x4b800000, v190
	v_cndmask_b32_e32 v180, v190, v180, vcc
	v_rsq_f32_e32 v180, v180
	s_nop 0
	v_mul_f32_e32 v190, 0x45800000, v180
	v_cndmask_b32_e32 v180, v180, v190, vcc
	v_mov_b32_e32 v190, v149
	v_mov_b32_e32 v149, v151
	v_mov_b32_e32 v151, v146
	v_pk_add_f32 v[148:149], v[190:191], v[148:149]
	v_pk_add_f32 v[144:145], v[150:151], v[144:145]
	v_mov_b32_e32 v147, v148
	v_mov_b32_e32 v146, v144
	v_mov_b32_e32 v148, v145
	v_pk_add_f32 v[144:145], v[146:147], v[148:149]
	ds_bpermute_b32 v147, v189, v145
	ds_bpermute_b32 v146, v189, v144
	v_mov_b32_e32 v148, v141
	v_mov_b32_e32 v149, v142
	v_mov_b32_e32 v141, v143
	v_mov_b32_e32 v142, v137
	v_mov_b32_e32 v143, v138
	v_mov_b32_e32 v137, v139
	v_pk_add_f32 v[140:141], v[148:149], v[140:141]
	v_pk_add_f32 v[136:137], v[142:143], v[136:137]
	s_waitcnt lgkmcnt(0)
	v_pk_add_f32 v[144:145], v[144:145], v[146:147]
	v_mov_b32_e32 v138, v136
	v_mov_b32_e32 v139, v140
	v_mov_b32_e32 v140, v137
	ds_bpermute_b32 v147, v188, v145
	ds_bpermute_b32 v146, v188, v144
	v_pk_add_f32 v[136:137], v[138:139], v[140:141]
	ds_bpermute_b32 v139, v189, v137
	ds_bpermute_b32 v138, v189, v136
	v_mov_b32_e32 v140, v133
	v_mov_b32_e32 v141, v134
	v_mov_b32_e32 v133, v135
	v_mov_b32_e32 v134, v129
	v_mov_b32_e32 v135, v130
	v_mov_b32_e32 v129, v131
	s_waitcnt lgkmcnt(2)
	v_pk_add_f32 v[144:145], v[144:145], v[146:147]
	v_pk_add_f32 v[132:133], v[140:141], v[132:133]
	v_pk_add_f32 v[128:129], v[134:135], v[128:129]
	v_pk_fma_f32 v[144:145], v[144:145], s[78:79], v[184:185] op_sel_hi:[1,0,0]
	s_waitcnt lgkmcnt(0)
	v_pk_add_f32 v[136:137], v[136:137], v[138:139]
	v_mov_b32_e32 v130, v128
	v_mov_b32_e32 v131, v132
	v_mov_b32_e32 v132, v129
	v_mul_f32_e32 v146, 0x4b800000, v145
	v_cmp_gt_f32_e64 s[8:9], s66, v145
	ds_bpermute_b32 v139, v188, v137
	ds_bpermute_b32 v138, v188, v136
	v_pk_add_f32 v[128:129], v[130:131], v[132:133]
	v_cndmask_b32_e64 v145, v145, v146, s[8:9]
	ds_bpermute_b32 v131, v189, v129
	ds_bpermute_b32 v130, v189, v128
	v_rsq_f32_e32 v145, v145
	s_waitcnt lgkmcnt(2)
	v_pk_add_f32 v[136:137], v[136:137], v[138:139]
	v_cmp_gt_f32_e32 vcc, s66, v144
	v_pk_fma_f32 v[136:137], v[136:137], s[78:79], v[184:185] op_sel_hi:[1,0,0]
	v_mul_f32_e32 v146, 0x45800000, v145
	s_waitcnt lgkmcnt(0)
	v_pk_add_f32 v[128:129], v[128:129], v[130:131]
	v_cndmask_b32_e64 v146, v145, v146, s[8:9]
	v_mul_f32_e32 v145, 0x4b800000, v144
	v_mul_f32_e32 v138, 0x4b800000, v137
	v_cmp_gt_f32_e64 s[8:9], s66, v137
	ds_bpermute_b32 v131, v188, v129
	ds_bpermute_b32 v130, v188, v128
	v_cndmask_b32_e32 v144, v144, v145, vcc
	v_cndmask_b32_e64 v137, v137, v138, s[8:9]
	v_rsq_f32_e32 v144, v144
	v_rsq_f32_e32 v137, v137
	s_waitcnt lgkmcnt(0)
	v_pk_add_f32 v[128:129], v[128:129], v[130:131]
	v_mul_f32_e32 v145, 0x45800000, v144
	v_mul_f32_e32 v138, 0x45800000, v137
	v_pk_fma_f32 v[128:129], v[128:129], s[78:79], v[184:185] op_sel_hi:[1,0,0]
	v_cndmask_b32_e32 v144, v144, v145, vcc
	v_cmp_gt_f32_e32 vcc, s66, v136
	v_cndmask_b32_e64 v138, v137, v138, s[8:9]
	v_mul_f32_e32 v137, 0x4b800000, v136
	v_mul_f32_e32 v130, 0x4b800000, v129
	v_cmp_gt_f32_e64 s[8:9], s66, v129
	v_cndmask_b32_e32 v136, v136, v137, vcc
	v_rsq_f32_e32 v136, v136
	v_cndmask_b32_e64 v129, v129, v130, s[8:9]
	v_rsq_f32_e32 v129, v129
	v_mul_f32_e32 v137, 0x45800000, v136
	v_cndmask_b32_e32 v136, v136, v137, vcc
	v_mul_f32_e32 v130, 0x45800000, v129
	v_cmp_gt_f32_e32 vcc, s66, v128
	v_cndmask_b32_e64 v142, v129, v130, s[8:9]
	v_mul_f32_e32 v129, 0x4b800000, v128
	v_cndmask_b32_e32 v128, v128, v129, vcc
	v_rsq_f32_e32 v128, v128
	s_mov_b64 s[8:9], -1
	v_mul_f32_e32 v129, 0x45800000, v128
	v_cndmask_b32_e32 v140, v128, v129, vcc
	s_cbranch_scc1 .LBB0_264
	s_andn2_b64 vcc, exec, s[8:9]
	s_cbranch_vccz .LBB0_459

.LBB0_926:
	s_or_b64 exec, exec, s[86:87]
	s_mov_b64 s[6:7], s[44:45]
	s_mov_b32 s8, -1
	s_waitcnt lgkmcnt(0)
	s_barrier
	s_mov_b32 s99, -1
	s_nop 0
	v_mbcnt_lo_u32_b32 v0, s8, 0
	v_mbcnt_hi_u32_b32 v0, s8, v0
	v_readlane_b32 s8, v255, 16
	v_or_b32_e32 v14, s33, v0
	v_readlane_b32 s9, v255, 17
	s_and_b64 vcc, exec, s[8:9]
	v_readfirstlane_b32 s14, v14
	s_cbranch_vccz .LBB0_942
	v_lshlrev_b32_e32 v0, 4, v14
	v_add_u32_e32 v1, 0x2000, v0
	v_ashrrev_i32_e32 v2, 31, v1
	v_lshrrev_b32_e32 v2, 22, v2
	v_add_u32_e32 v2, v1, v2
	v_ashrrev_i32_e32 v8, 10, v2
	v_mul_i32_i24_e32 v2, 0x400, v8
	v_sub_u32_e32 v1, v1, v2
	v_lshrrev_b32_e32 v2, 4, v1
	v_bitop3_b32 v1, v2, v1, 32 bitop3:0x6c
	v_ashrrev_i32_e32 v2, 31, v1
	s_add_u32 s30, s6, 0x6900000
	v_lshrrev_b32_e32 v2, 26, v2
	s_addc_u32 s31, s7, 0
	v_add_u32_e32 v2, v1, v2
	v_lshlrev_b32_e32 v3, 3, v8
	s_add_u32 s8, s6, s1
	v_readlane_b32 s9, v255, 42
	v_ashrrev_i32_e32 v9, 6, v2
	v_and_b32_e32 v3, -16, v3
	s_addc_u32 s9, s7, s9
	v_add_u32_e32 v3, v9, v3
	s_add_u32 s34, s8, 0xa80000
	v_and_b32_e32 v4, 3, v9
	s_mov_b32 s8, 0x1fffe0
	v_lshrrev_b32_e32 v5, 2, v3
	v_lshlrev_b32_e32 v6, 1, v3
	v_and_b32_e32 v2, 0xc0, v2
	v_and_or_b32 v4, v3, s8, v4
	v_and_b32_e32 v5, 4, v5
	v_and_b32_e32 v6, 24, v6
	v_sub_u32_e32 v1, v1, v2
	v_or3_b32 v4, v4, v5, v6
	v_lshlrev_b32_e32 v5, 5, v8
	v_ashrrev_i16_sdwa v1, v237, sext(v1) dst_sel:DWORD dst_unused:UNUSED_PAD src0_sel:DWORD src1_sel:BYTE_0
	v_and_b32_e32 v5, 32, v5
	v_bfe_i32 v10, v1, 0, 16
	v_add_lshl_u32 v1, v5, v10, 1
	v_lshl_add_u32 v152, v4, 11, v1
	v_lshl_add_u32 v154, v3, 11, v1
	v_bfe_i32 v1, v14, 27, 1
	v_lshrrev_b32_e32 v1, 22, v1
	v_add_u32_e32 v1, v0, v1
	v_and_b32_e32 v1, 0xfffffc00, v1
	v_sub_u32_e32 v0, v0, v1
	v_lshrrev_b32_e32 v1, 4, v0
	v_ashrrev_i32_e32 v2, 31, v14
	v_bitop3_b32 v0, v1, v0, 32 bitop3:0x6c
	v_lshrrev_b32_e32 v2, 26, v2
	v_ashrrev_i32_e32 v1, 31, v0
	v_add_u32_e32 v2, v14, v2
	v_lshrrev_b32_e32 v1, 26, v1
	v_ashrrev_i32_e32 v12, 6, v2
	v_add_u32_e32 v1, v0, v1
	v_lshlrev_b32_e32 v2, 3, v12
	v_ashrrev_i32_e32 v11, 6, v1
	v_and_b32_e32 v2, -16, v2
	v_add_u32_e32 v2, v11, v2
	v_and_b32_e32 v3, 3, v11
	v_lshrrev_b32_e32 v4, 2, v2
	v_lshlrev_b32_e32 v5, 1, v2
	v_and_b32_e32 v1, 0xc0, v1
	s_addc_u32 s35, s9, 0
	s_ashr_i32 s15, s14, 6
	v_and_or_b32 v3, v2, s8, v3
	v_and_b32_e32 v4, 4, v4
	v_and_b32_e32 v5, 24, v5
	v_sub_u32_e32 v0, v0, v1
	s_ashr_i32 s18, s14, 8
	s_lshl_b32 s36, s15, 10
	v_or3_b32 v3, v3, v4, v5
	v_lshlrev_b32_e32 v4, 5, v12
	v_ashrrev_i16_sdwa v0, v237, sext(v0) dst_sel:DWORD dst_unused:UNUSED_PAD src0_sel:DWORD src1_sel:BYTE_0
	v_readlane_b32 s8, v255, 21
	v_and_b32_e32 v4, 32, v4
	v_bfe_i32 v13, v0, 0, 16
	v_readlane_b32 s9, v255, 22
	s_add_u32 s8, s34, s8
	v_add_lshl_u32 v0, v4, v13, 1
	s_addc_u32 s9, s35, s9
	s_add_i32 s37, s36, 0
	v_lshl_add_u32 v192, v3, 11, v0
	s_add_i32 m0, s37, 0x10000
	v_lshl_add_u32 v156, v2, 11, v0
	global_load_lds_dwordx4 v192, s[8:9]
	s_add_i32 m0, s37, 0x12000
	s_add_u32 s10, s8, 0x40000
	global_load_lds_dwordx4 v152, s[8:9]
	s_addc_u32 s11, s9, 0
	s_add_i32 m0, s37, 0x14000
	v_mov_b32_e32 v153, v193
	global_load_lds_dwordx4 v192, s[10:11]
	s_add_i32 m0, s37, 0x16000
	v_mov_b32_e32 v157, v193
	global_load_lds_dwordx4 v152, s[10:11]
	v_readlane_b32 s10, v255, 32
	v_readlane_b32 s11, v255, 33
	s_add_u32 s26, s30, s10
	s_addc_u32 s27, s31, s11
	s_add_i32 s38, s37, 0x2000
	s_mov_b32 m0, s37
	s_add_u32 s10, s26, 0x40000
	global_load_lds_dwordx4 v156, s[26:27]
	s_mov_b32 m0, s38
	s_addc_u32 s11, s27, 0
	s_add_i32 s39, s37, 0x4000
	global_load_lds_dwordx4 v154, s[26:27]
	s_mov_b32 m0, s39
	s_add_i32 s46, s37, 0x6000
	global_load_lds_dwordx4 v156, s[10:11]
	s_mov_b32 m0, s46
	v_mov_b32_e32 v155, v193
	global_load_lds_dwordx4 v154, s[10:11]
	s_cmp_eq_u32 s18, 1
	v_lshl_add_u64 v[6:7], s[8:9], 0, v[192:193]
	v_lshl_add_u64 v[4:5], s[8:9], 0, v[152:153]
	v_lshl_add_u64 v[0:1], s[26:27], 0, v[156:157]
	s_cselect_b64 s[10:11], -1, 0
	s_cmp_lg_u32 s18, 1
	v_lshl_add_u64 v[2:3], s[26:27], 0, v[154:155]
	s_cbranch_scc1 .LBB0_929
	s_barrier

.LBB0_938:
	s_cmp_eq_u32 s51, s99
	s_cbranch_scc1 .Lp8_rr_hit
	v_lshl_add_u32 v178, s51, 8, v183
	v_ashrrev_i32_e32 v179, 31, v178
	v_lshlrev_b64 v[128:129], 6, v[178:179]
	v_or_b32_e32 v176, 16, v178
	v_lshl_add_u64 v[128:129], v[158:159], 0, v[128:129]
	v_ashrrev_i32_e32 v177, 31, v176
	global_load_dwordx4 v[202:205], v[128:129], off
	v_lshlrev_b64 v[128:129], 6, v[176:177]
	v_lshl_add_u64 v[128:129], v[158:159], 0, v[128:129]
	global_load_dwordx4 v[206:209], v[128:129], off
	v_or_b32_e32 v174, 32, v178
	v_ashrrev_i32_e32 v175, 31, v174
	v_lshlrev_b64 v[128:129], 6, v[174:175]
	v_or_b32_e32 v172, 48, v178
	v_lshl_add_u64 v[128:129], v[158:159], 0, v[128:129]
	v_ashrrev_i32_e32 v173, 31, v172
	global_load_dwordx4 v[148:151], v[128:129], off
	v_lshlrev_b64 v[128:129], 6, v[172:173]
	v_lshl_add_u64 v[128:129], v[158:159], 0, v[128:129]
	global_load_dwordx4 v[144:147], v[128:129], off
	v_add_u32_e32 v170, 0x80, v178
	v_ashrrev_i32_e32 v171, 31, v170
	v_lshlrev_b64 v[128:129], 6, v[170:171]
	v_add_u32_e32 v168, 0x90, v178
	v_lshl_add_u64 v[128:129], v[158:159], 0, v[128:129]
	v_ashrrev_i32_e32 v169, 31, v168
	global_load_dwordx4 v[140:143], v[128:129], off
	v_lshlrev_b64 v[128:129], 6, v[168:169]
	v_lshl_add_u64 v[128:129], v[158:159], 0, v[128:129]
	global_load_dwordx4 v[136:139], v[128:129], off
	v_add_u32_e32 v166, 0xa0, v178
	v_ashrrev_i32_e32 v167, 31, v166
	v_lshlrev_b64 v[128:129], 6, v[166:167]
	v_add_u32_e32 v164, 0xb0, v178
	v_lshl_add_u64 v[128:129], v[158:159], 0, v[128:129]
	v_ashrrev_i32_e32 v165, 31, v164
	global_load_dwordx4 v[132:135], v[128:129], off
	v_lshlrev_b64 v[128:129], 6, v[164:165]
	v_lshl_add_u64 v[128:129], v[158:159], 0, v[128:129]
	global_load_dwordx4 v[128:131], v[128:129], off
	v_and_b32_e32 v167, 64, v239
	v_xor_b32_e32 v165, 16, v239
	v_add_u32_e32 v169, 64, v167
	v_cmp_lt_i32_e32 vcc, v165, v169
	v_lshl_or_b32 v180, s50, 7, v188
	v_ashrrev_i32_e32 v181, 31, v180
	v_cndmask_b32_e32 v165, v239, v165, vcc
	v_lshlrev_b32_e32 v167, 2, v165
	v_xor_b32_e32 v165, 32, v239
	v_cmp_lt_i32_e32 vcc, v165, v169
	s_movk_i32 s82, 0x180
	s_waitcnt vmcnt(0)
	v_add_f32_e32 v247, v202, v203
	v_add_f32_e32 v248, v204, v205
	v_add_f32_e32 v230, v247, v248
	v_add_f32_e32 v249, v206, v207
	v_add_f32_e32 v250, v208, v209
	v_add_f32_e32 v231, v249, v250
	v_add_f32_e32 v247, v148, v149
	v_add_f32_e32 v248, v150, v151
	v_add_f32_e32 v232, v247, v248
	v_add_f32_e32 v249, v144, v145
	v_add_f32_e32 v250, v146, v147
	v_add_f32_e32 v233, v249, v250
	v_add_f32_e32 v247, v140, v141
	v_add_f32_e32 v248, v142, v143
	v_add_f32_e32 v234, v247, v248
	v_add_f32_e32 v249, v136, v137
	v_add_f32_e32 v250, v138, v139
	v_add_f32_e32 v235, v249, v250
	v_add_f32_e32 v247, v132, v133
	v_add_f32_e32 v248, v134, v135
	v_add_f32_e32 v242, v247, v248
	v_add_f32_e32 v249, v128, v129
	v_add_f32_e32 v250, v130, v131
	v_add_f32_e32 v243, v249, v250
	s_mov_b32 s99, s51
	s_branch .Lp8_rr_join
.Lp8_rr_hit:
	v_lshl_add_u32 v178, s51, 8, v183
	v_ashrrev_i32_e32 v179, 31, v178
	v_lshlrev_b64 v[128:129], 6, v[178:179]
	v_or_b32_e32 v176, 16, v178
	v_lshl_add_u64 v[128:129], v[158:159], 0, v[128:129]
	v_ashrrev_i32_e32 v177, 31, v176
	v_lshlrev_b64 v[128:129], 6, v[176:177]
	v_lshl_add_u64 v[128:129], v[158:159], 0, v[128:129]
	v_or_b32_e32 v174, 32, v178
	v_ashrrev_i32_e32 v175, 31, v174
	v_lshlrev_b64 v[128:129], 6, v[174:175]
	v_or_b32_e32 v172, 48, v178
	v_lshl_add_u64 v[128:129], v[158:159], 0, v[128:129]
	v_ashrrev_i32_e32 v173, 31, v172
	v_lshlrev_b64 v[128:129], 6, v[172:173]
	v_lshl_add_u64 v[128:129], v[158:159], 0, v[128:129]
	v_add_u32_e32 v170, 0x80, v178
	v_ashrrev_i32_e32 v171, 31, v170
	v_lshlrev_b64 v[128:129], 6, v[170:171]
	v_add_u32_e32 v168, 0x90, v178
	v_lshl_add_u64 v[128:129], v[158:159], 0, v[128:129]
	v_ashrrev_i32_e32 v169, 31, v168
	v_lshlrev_b64 v[128:129], 6, v[168:169]
	v_lshl_add_u64 v[128:129], v[158:159], 0, v[128:129]
	v_add_u32_e32 v166, 0xa0, v178
	v_ashrrev_i32_e32 v167, 31, v166
	v_lshlrev_b64 v[128:129], 6, v[166:167]
	v_add_u32_e32 v164, 0xb0, v178
	v_lshl_add_u64 v[128:129], v[158:159], 0, v[128:129]
	v_ashrrev_i32_e32 v165, 31, v164
	v_lshlrev_b64 v[128:129], 6, v[164:165]
	v_lshl_add_u64 v[128:129], v[158:159], 0, v[128:129]
	v_and_b32_e32 v167, 64, v239
	v_xor_b32_e32 v165, 16, v239
	v_add_u32_e32 v169, 64, v167
	v_cmp_lt_i32_e32 vcc, v165, v169
	v_lshl_or_b32 v180, s50, 7, v188
	v_ashrrev_i32_e32 v181, 31, v180
	v_cndmask_b32_e32 v165, v239, v165, vcc
	v_lshlrev_b32_e32 v167, 2, v165
	v_xor_b32_e32 v165, 32, v239
	v_cmp_lt_i32_e32 vcc, v165, v169
	s_movk_i32 s82, 0x180
	v_mov_b32_e32 v202, v230
	v_mov_b32_e32 v203, 0
	v_mov_b64_e32 v[204:205], 0
	v_mov_b32_e32 v206, v231
	v_mov_b32_e32 v207, 0
	v_mov_b64_e32 v[208:209], 0
	v_mov_b32_e32 v148, v232
	v_mov_b32_e32 v149, 0
	v_mov_b64_e32 v[150:151], 0
	v_mov_b32_e32 v144, v233
	v_mov_b32_e32 v145, 0
	v_mov_b64_e32 v[146:147], 0
	v_mov_b32_e32 v140, v234
	v_mov_b32_e32 v141, 0
	v_mov_b64_e32 v[142:143], 0
	v_mov_b32_e32 v136, v235
	v_mov_b32_e32 v137, 0
	v_mov_b64_e32 v[138:139], 0
	v_mov_b32_e32 v132, v242
	v_mov_b32_e32 v133, 0
	v_mov_b64_e32 v[134:135], 0
	v_mov_b32_e32 v128, v243
	v_mov_b32_e32 v129, 0
	v_mov_b64_e32 v[130:131], 0
.Lp8_rr_join:
	v_mov_b32_e32 v186, v203
	v_mov_b32_e32 v187, v204
	v_mov_b32_e32 v203, v205
	v_mov_b32_e32 v190, v207
	v_mov_b32_e32 v191, v208
	v_mov_b32_e32 v207, v209
	v_pk_add_f32 v[186:187], v[186:187], v[202:203]
	v_pk_add_f32 v[190:191], v[190:191], v[206:207]
	v_mov_b32_e32 v203, v186
	v_mov_b32_e32 v202, v190
	v_mov_b32_e32 v186, v191
	v_pk_add_f32 v[186:187], v[202:203], v[186:187]
	ds_bpermute_b32 v191, v167, v187
	ds_bpermute_b32 v190, v167, v186
	v_cndmask_b32_e32 v165, v239, v165, vcc
	v_lshlrev_b32_e32 v165, 2, v165
	s_waitcnt lgkmcnt(0)
	v_pk_add_f32 v[186:187], v[186:187], v[190:191]
	ds_bpermute_b32 v191, v165, v187
	ds_bpermute_b32 v190, v165, v186
	s_waitcnt lgkmcnt(0)
	v_pk_add_f32 v[190:191], v[186:187], v[190:191]
	v_mov_b64_e32 v[186:187], s[80:81]
	v_pk_fma_f32 v[190:191], v[190:191], s[78:79], v[186:187] op_sel_hi:[1,0,0]
	s_nop 0
	v_mul_f32_e32 v169, 0x4b800000, v191
	v_cmp_gt_f32_e64 s[8:9], s66, v191
	v_cmp_gt_f32_e32 vcc, s66, v190
	s_nop 0
	v_cndmask_b32_e64 v169, v191, v169, s[8:9]
	v_rsq_f32_e32 v169, v169
	v_mov_b32_e32 v191, v150
	v_mov_b32_e32 v150, v145
	v_mov_b32_e32 v145, v147
	v_mul_f32_e32 v171, 0x45800000, v169
	v_cndmask_b32_e64 v184, v169, v171, s[8:9]
	v_mul_f32_e32 v169, 0x4b800000, v190
	v_cndmask_b32_e32 v169, v190, v169, vcc
	v_mov_b32_e32 v190, v149
	v_mov_b32_e32 v149, v151
	v_mov_b32_e32 v151, v146
	v_pk_add_f32 v[148:149], v[190:191], v[148:149]
	v_pk_add_f32 v[144:145], v[150:151], v[144:145]
	v_mov_b32_e32 v147, v148
	v_mov_b32_e32 v146, v144
	v_mov_b32_e32 v148, v145
	v_pk_add_f32 v[144:145], v[146:147], v[148:149]
	ds_bpermute_b32 v147, v167, v145
	ds_bpermute_b32 v146, v167, v144
	v_mov_b32_e32 v148, v141
	v_mov_b32_e32 v149, v142
	v_mov_b32_e32 v141, v143
	v_mov_b32_e32 v142, v137
	v_mov_b32_e32 v143, v138
	v_mov_b32_e32 v137, v139
	v_pk_add_f32 v[140:141], v[148:149], v[140:141]
	v_pk_add_f32 v[136:137], v[142:143], v[136:137]
	s_waitcnt lgkmcnt(0)
	v_pk_add_f32 v[144:145], v[144:145], v[146:147]
	v_mov_b32_e32 v138, v136
	v_mov_b32_e32 v139, v140
	v_mov_b32_e32 v140, v137
	ds_bpermute_b32 v147, v165, v145
	ds_bpermute_b32 v146, v165, v144
	v_pk_add_f32 v[136:137], v[138:139], v[140:141]
	ds_bpermute_b32 v139, v167, v137
	ds_bpermute_b32 v138, v167, v136
	v_mov_b32_e32 v140, v133
	v_mov_b32_e32 v141, v134
	v_mov_b32_e32 v133, v135
	v_mov_b32_e32 v134, v129
	v_mov_b32_e32 v135, v130
	v_mov_b32_e32 v129, v131
	s_waitcnt lgkmcnt(2)
	v_pk_add_f32 v[144:145], v[144:145], v[146:147]
	v_pk_add_f32 v[132:133], v[140:141], v[132:133]
	v_pk_add_f32 v[128:129], v[134:135], v[128:129]
	v_pk_fma_f32 v[144:145], v[144:145], s[78:79], v[186:187] op_sel_hi:[1,0,0]
	s_waitcnt lgkmcnt(0)
	v_pk_add_f32 v[136:137], v[136:137], v[138:139]
	v_mov_b32_e32 v130, v128
	v_mov_b32_e32 v131, v132
	v_mov_b32_e32 v132, v129
	v_mul_f32_e32 v146, 0x4b800000, v145
	v_cmp_gt_f32_e64 s[8:9], s66, v145
	ds_bpermute_b32 v139, v165, v137
	ds_bpermute_b32 v138, v165, v136
	v_pk_add_f32 v[128:129], v[130:131], v[132:133]
	v_cndmask_b32_e64 v145, v145, v146, s[8:9]
	ds_bpermute_b32 v131, v167, v129
	ds_bpermute_b32 v130, v167, v128
	v_rsq_f32_e32 v169, v169
	v_rsq_f32_e32 v145, v145
	s_waitcnt lgkmcnt(2)
	v_pk_add_f32 v[136:137], v[136:137], v[138:139]
	v_pk_mul_f32 v[124:125], v[124:125], v[184:185] op_sel_hi:[1,0]
	v_mul_f32_e32 v171, 0x45800000, v169
	v_mul_f32_e32 v146, 0x45800000, v145
	v_pk_fma_f32 v[136:137], v[136:137], s[78:79], v[186:187] op_sel_hi:[1,0,0]
	s_waitcnt lgkmcnt(0)
	v_pk_add_f32 v[128:129], v[128:129], v[130:131]
	v_cndmask_b32_e32 v182, v169, v171, vcc
	v_cmp_gt_f32_e32 vcc, s66, v144
	v_cndmask_b32_e64 v146, v145, v146, s[8:9]
	v_mul_f32_e32 v145, 0x4b800000, v144
	v_mul_f32_e32 v138, 0x4b800000, v137
	v_cmp_gt_f32_e64 s[8:9], s66, v137
	ds_bpermute_b32 v131, v165, v129
	ds_bpermute_b32 v130, v165, v128
	v_cndmask_b32_e32 v144, v144, v145, vcc
	v_cndmask_b32_e64 v137, v137, v138, s[8:9]
	v_rsq_f32_e32 v144, v144
	v_rsq_f32_e32 v137, v137
	s_waitcnt lgkmcnt(0)
	v_pk_add_f32 v[128:129], v[128:129], v[130:131]
	v_pk_mul_f32 v[120:121], v[120:121], v[184:185] op_sel_hi:[1,0]
	v_mul_f32_e32 v145, 0x45800000, v144
	v_mul_f32_e32 v138, 0x45800000, v137
	v_pk_fma_f32 v[128:129], v[128:129], s[78:79], v[186:187] op_sel_hi:[1,0,0]
	v_cndmask_b32_e32 v144, v144, v145, vcc
	v_cmp_gt_f32_e32 vcc, s66, v136
	v_cndmask_b32_e64 v138, v137, v138, s[8:9]
	v_mul_f32_e32 v137, 0x4b800000, v136
	v_mul_f32_e32 v130, 0x4b800000, v129
	v_cmp_gt_f32_e64 s[8:9], s66, v129
	v_cndmask_b32_e32 v136, v136, v137, vcc
	v_rsq_f32_e32 v136, v136
	v_cndmask_b32_e64 v129, v129, v130, s[8:9]
	v_rsq_f32_e32 v129, v129
	v_pk_mul_f32 v[122:123], v[122:123], v[184:185] op_sel_hi:[1,0]
	v_mul_f32_e32 v137, 0x45800000, v136
	v_cndmask_b32_e32 v136, v136, v137, vcc
	v_mul_f32_e32 v130, 0x45800000, v129
	v_cmp_gt_f32_e32 vcc, s66, v128
	v_cndmask_b32_e64 v130, v129, v130, s[8:9]
	v_mul_f32_e32 v129, 0x4b800000, v128
	v_cndmask_b32_e32 v128, v128, v129, vcc
	v_rsq_f32_e32 v128, v128
	v_pk_mul_f32 v[116:117], v[116:117], v[184:185] op_sel_hi:[1,0]
	v_pk_mul_f32 v[112:113], v[112:113], v[184:185] op_sel_hi:[1,0]
	v_pk_mul_f32 v[114:115], v[114:115], v[184:185] op_sel_hi:[1,0]
	v_mul_f32_e32 v129, 0x45800000, v128
	v_cndmask_b32_e32 v128, v128, v129, vcc
	v_mul_f32_e32 v129, 0xbfb8aa3b, v124
	v_exp_f32_e32 v129, v129
	v_pk_mul_f32 v[108:109], v[108:109], v[182:183] op_sel_hi:[1,0]
	v_pk_mul_f32 v[104:105], v[104:105], v[182:183] op_sel_hi:[1,0]
	v_pk_mul_f32 v[106:107], v[106:107], v[182:183] op_sel_hi:[1,0]
	v_add_f32_e32 v129, 1.0, v129
	v_rcp_f32_e32 v132, v129
	v_mul_f32_e32 v129, 0xbfb8aa3b, v125
	v_exp_f32_e32 v129, v129
	v_pk_mul_f32 v[100:101], v[100:101], v[182:183] op_sel_hi:[1,0]
	v_pk_mul_f32 v[96:97], v[96:97], v[182:183] op_sel_hi:[1,0]
	v_pk_mul_f32 v[98:99], v[98:99], v[182:183] op_sel_hi:[1,0]
	v_add_f32_e32 v129, 1.0, v129
	v_rcp_f32_e32 v133, v129
	v_pk_mul_f32 v[92:93], v[92:93], v[146:147] op_sel_hi:[1,0]
	v_pk_mul_f32 v[88:89], v[88:89], v[146:147] op_sel_hi:[1,0]
	v_pk_mul_f32 v[90:91], v[90:91], v[146:147] op_sel_hi:[1,0]
	v_pk_mul_f32 v[124:125], v[124:125], v[132:133]
	v_pk_mul_f32 v[84:85], v[84:85], v[146:147] op_sel_hi:[1,0]
	v_pk_mul_f32 v[120:121], v[120:121], v[124:125]
	v_pk_mul_f32 v[124:125], v[126:127], v[184:185] op_sel_hi:[1,0]
	v_pk_mul_f32 v[80:81], v[80:81], v[146:147] op_sel_hi:[1,0]
	v_mul_f32_e32 v126, 0xbfb8aa3b, v124
	v_mul_f32_e32 v127, 0xbfb8aa3b, v125
	v_exp_f32_e32 v126, v126
	v_exp_f32_e32 v127, v127
	v_pk_mul_f32 v[82:83], v[82:83], v[146:147] op_sel_hi:[1,0]
	v_pk_mul_f32 v[76:77], v[76:77], v[144:145] op_sel_hi:[1,0]
	v_add_f32_e32 v126, 1.0, v126
	v_add_f32_e32 v127, 1.0, v127
	v_rcp_f32_e32 v126, v126
	v_rcp_f32_e32 v127, v127
	v_pk_mul_f32 v[72:73], v[72:73], v[144:145] op_sel_hi:[1,0]
	v_pk_mul_f32 v[74:75], v[74:75], v[144:145] op_sel_hi:[1,0]
	v_pk_mul_f32 v[68:69], v[68:69], v[144:145] op_sel_hi:[1,0]
	v_pk_mul_f32 v[124:125], v[124:125], v[126:127]
	v_pk_mul_f32 v[64:65], v[64:65], v[144:145] op_sel_hi:[1,0]
	v_pk_mul_f32 v[122:123], v[122:123], v[124:125]
	v_mul_f32_e32 v124, 0xbfb8aa3b, v116
	v_mul_f32_e32 v125, 0xbfb8aa3b, v117
	v_exp_f32_e32 v124, v124
	v_exp_f32_e32 v125, v125
	v_pk_mul_f32 v[66:67], v[66:67], v[144:145] op_sel_hi:[1,0]
	v_pk_mul_f32 v[60:61], v[60:61], v[138:139] op_sel_hi:[1,0]
	v_add_f32_e32 v124, 1.0, v124
	v_add_f32_e32 v125, 1.0, v125
	v_rcp_f32_e32 v124, v124
	v_rcp_f32_e32 v125, v125
	v_pk_mul_f32 v[56:57], v[56:57], v[138:139] op_sel_hi:[1,0]
	v_pk_mul_f32 v[58:59], v[58:59], v[138:139] op_sel_hi:[1,0]
	v_pk_mul_f32 v[52:53], v[52:53], v[138:139] op_sel_hi:[1,0]
	v_pk_mul_f32 v[116:117], v[116:117], v[124:125]
	v_pk_mul_f32 v[48:49], v[48:49], v[138:139] op_sel_hi:[1,0]
	v_pk_mul_f32 v[112:113], v[112:113], v[116:117]
	v_pk_mul_f32 v[116:117], v[118:119], v[184:185] op_sel_hi:[1,0]
	v_pk_mul_f32 v[50:51], v[50:51], v[138:139] op_sel_hi:[1,0]
	v_mul_f32_e32 v118, 0xbfb8aa3b, v116
	v_mul_f32_e32 v119, 0xbfb8aa3b, v117
	v_exp_f32_e32 v118, v118
	v_exp_f32_e32 v119, v119
	v_pk_mul_f32 v[44:45], v[44:45], v[136:137] op_sel_hi:[1,0]
	v_pk_mul_f32 v[40:41], v[40:41], v[136:137] op_sel_hi:[1,0]
	v_add_f32_e32 v118, 1.0, v118
	v_add_f32_e32 v119, 1.0, v119
	v_rcp_f32_e32 v118, v118
	v_rcp_f32_e32 v119, v119
	v_pk_mul_f32 v[42:43], v[42:43], v[136:137] op_sel_hi:[1,0]
	v_pk_mul_f32 v[36:37], v[36:37], v[136:137] op_sel_hi:[1,0]
	v_pk_mul_f32 v[32:33], v[32:33], v[136:137] op_sel_hi:[1,0]
	v_pk_mul_f32 v[116:117], v[116:117], v[118:119]
	v_cvt_pk_bf16_f32 v118, v112, v113
	v_pk_mul_f32 v[114:115], v[114:115], v[116:117]
	v_mov_b64_e32 v[112:113], s[12:13]
	v_cvt_pk_bf16_f32 v116, v120, v121
	v_cvt_pk_bf16_f32 v119, v114, v115
	v_mad_i64_i32 v[120:121], s[8:9], v178, s3, v[112:113]
	v_lshlrev_b64 v[114:115], 1, v[180:181]
	v_cvt_pk_bf16_f32 v117, v122, v123
	v_lshl_add_u64 v[120:121], v[120:121], 0, v[114:115]
	global_store_dwordx4 v[120:121], v[116:119], off
	v_pk_mul_f32 v[34:35], v[34:35], v[136:137] op_sel_hi:[1,0]
	v_pk_mul_f32 v[28:29], v[28:29], v[130:131] op_sel_hi:[1,0]
	v_mul_f32_e32 v116, 0xbfb8aa3b, v108
	v_mul_f32_e32 v117, 0xbfb8aa3b, v109
	v_exp_f32_e32 v116, v116
	v_exp_f32_e32 v117, v117
	v_pk_mul_f32 v[24:25], v[24:25], v[130:131] op_sel_hi:[1,0]
	v_pk_mul_f32 v[26:27], v[26:27], v[130:131] op_sel_hi:[1,0]
	v_add_f32_e32 v116, 1.0, v116
	v_add_f32_e32 v117, 1.0, v117
	v_rcp_f32_e32 v116, v116
	v_rcp_f32_e32 v117, v117
	v_pk_mul_f32 v[20:21], v[20:21], v[130:131] op_sel_hi:[1,0]
	v_pk_mul_f32 v[16:17], v[16:17], v[130:131] op_sel_hi:[1,0]
	v_pk_mul_f32 v[18:19], v[18:19], v[130:131] op_sel_hi:[1,0]
	v_pk_mul_f32 v[108:109], v[108:109], v[116:117]
	v_pk_mul_f32 v[12:13], v[12:13], v[128:129] op_sel_hi:[1,0]
	v_pk_mul_f32 v[104:105], v[104:105], v[108:109]
	v_pk_mul_f32 v[108:109], v[110:111], v[182:183] op_sel_hi:[1,0]
	v_pk_mul_f32 v[8:9], v[8:9], v[128:129] op_sel_hi:[1,0]
	v_mul_f32_e32 v110, 0xbfb8aa3b, v108
	v_mul_f32_e32 v111, 0xbfb8aa3b, v109
	v_exp_f32_e32 v110, v110
	v_exp_f32_e32 v111, v111
	v_pk_mul_f32 v[10:11], v[10:11], v[128:129] op_sel_hi:[1,0]
	v_pk_mul_f32 v[4:5], v[4:5], v[128:129] op_sel_hi:[1,0]
	v_add_f32_e32 v110, 1.0, v110
	v_add_f32_e32 v111, 1.0, v111
	v_rcp_f32_e32 v110, v110
	v_rcp_f32_e32 v111, v111
	v_pk_mul_f32 v[0:1], v[0:1], v[128:129] op_sel_hi:[1,0]
	v_pk_mul_f32 v[2:3], v[2:3], v[128:129] op_sel_hi:[1,0]
	s_andn2_b64 vcc, exec, s[6:7]
	v_pk_mul_f32 v[108:109], v[108:109], v[110:111]
	s_nop 0
	v_pk_mul_f32 v[106:107], v[106:107], v[108:109]
	v_mul_f32_e32 v108, 0xbfb8aa3b, v100
	v_mul_f32_e32 v109, 0xbfb8aa3b, v101
	v_exp_f32_e32 v108, v108
	v_exp_f32_e32 v109, v109
	v_add_f32_e32 v108, 1.0, v108
	v_add_f32_e32 v109, 1.0, v109
	v_rcp_f32_e32 v108, v108
	v_rcp_f32_e32 v109, v109
	s_nop 0
	v_pk_mul_f32 v[100:101], v[100:101], v[108:109]
	s_nop 0
	v_pk_mul_f32 v[100:101], v[96:97], v[100:101]
	v_pk_mul_f32 v[96:97], v[102:103], v[182:183] op_sel_hi:[1,0]
	s_nop 0
	v_mul_f32_e32 v102, 0xbfb8aa3b, v96
	v_mul_f32_e32 v103, 0xbfb8aa3b, v97
	v_exp_f32_e32 v102, v102
	v_exp_f32_e32 v103, v103
	v_add_f32_e32 v102, 1.0, v102
	v_add_f32_e32 v103, 1.0, v103
	v_rcp_f32_e32 v102, v102
	v_rcp_f32_e32 v103, v103
	s_nop 0
	v_pk_mul_f32 v[96:97], v[96:97], v[102:103]
	s_nop 0
	v_pk_mul_f32 v[102:103], v[98:99], v[96:97]
	v_cvt_pk_bf16_f32 v98, v100, v101
	v_mad_i64_i32 v[100:101], s[8:9], v176, s3, v[112:113]
	v_cvt_pk_bf16_f32 v96, v104, v105
	v_cvt_pk_bf16_f32 v97, v106, v107
	v_cvt_pk_bf16_f32 v99, v102, v103
	v_lshl_add_u64 v[100:101], v[100:101], 0, v[114:115]
	global_store_dwordx4 v[100:101], v[96:99], off
	s_nop 1
	v_mul_f32_e32 v96, 0xbfb8aa3b, v92
	v_mul_f32_e32 v97, 0xbfb8aa3b, v93
	v_exp_f32_e32 v96, v96
	v_exp_f32_e32 v97, v97
	v_add_f32_e32 v96, 1.0, v96
	v_add_f32_e32 v97, 1.0, v97
	v_rcp_f32_e32 v96, v96
	v_rcp_f32_e32 v97, v97
	s_nop 0
	v_pk_mul_f32 v[92:93], v[92:93], v[96:97]
	s_nop 0
	v_pk_mul_f32 v[88:89], v[88:89], v[92:93]
	v_pk_mul_f32 v[92:93], v[94:95], v[146:147] op_sel_hi:[1,0]
	s_nop 0
	v_mul_f32_e32 v94, 0xbfb8aa3b, v92
	v_mul_f32_e32 v95, 0xbfb8aa3b, v93
	v_exp_f32_e32 v94, v94
	v_exp_f32_e32 v95, v95
	v_add_f32_e32 v94, 1.0, v94
	v_add_f32_e32 v95, 1.0, v95
	v_rcp_f32_e32 v94, v94
	v_rcp_f32_e32 v95, v95
	s_nop 0
	v_pk_mul_f32 v[92:93], v[92:93], v[94:95]
	s_nop 0
	v_pk_mul_f32 v[90:91], v[90:91], v[92:93]
	v_mul_f32_e32 v92, 0xbfb8aa3b, v84
	v_mul_f32_e32 v93, 0xbfb8aa3b, v85
	v_exp_f32_e32 v92, v92
	v_exp_f32_e32 v93, v93
	v_add_f32_e32 v92, 1.0, v92
	v_add_f32_e32 v93, 1.0, v93
	v_rcp_f32_e32 v92, v92
	v_rcp_f32_e32 v93, v93
	s_nop 0
	v_pk_mul_f32 v[84:85], v[84:85], v[92:93]
	s_nop 0
	v_pk_mul_f32 v[84:85], v[80:81], v[84:85]
	v_pk_mul_f32 v[80:81], v[86:87], v[146:147] op_sel_hi:[1,0]
	s_nop 0
	v_mul_f32_e32 v86, 0xbfb8aa3b, v80
	v_mul_f32_e32 v87, 0xbfb8aa3b, v81
	v_exp_f32_e32 v86, v86
	v_exp_f32_e32 v87, v87
	v_add_f32_e32 v86, 1.0, v86
	v_add_f32_e32 v87, 1.0, v87
	v_rcp_f32_e32 v86, v86
	v_rcp_f32_e32 v87, v87
	s_nop 0
	v_pk_mul_f32 v[80:81], v[80:81], v[86:87]
	s_nop 0
	v_pk_mul_f32 v[86:87], v[82:83], v[80:81]
	v_cvt_pk_bf16_f32 v82, v84, v85
	v_mad_i64_i32 v[84:85], s[8:9], v174, s3, v[112:113]
	v_cvt_pk_bf16_f32 v80, v88, v89
	v_cvt_pk_bf16_f32 v81, v90, v91
	v_cvt_pk_bf16_f32 v83, v86, v87
	v_lshl_add_u64 v[84:85], v[84:85], 0, v[114:115]
	global_store_dwordx4 v[84:85], v[80:83], off
	s_nop 1
	v_mul_f32_e32 v80, 0xbfb8aa3b, v76
	v_mul_f32_e32 v81, 0xbfb8aa3b, v77
	v_exp_f32_e32 v80, v80
	v_exp_f32_e32 v81, v81
	v_add_f32_e32 v80, 1.0, v80
	v_add_f32_e32 v81, 1.0, v81
	v_rcp_f32_e32 v80, v80
	v_rcp_f32_e32 v81, v81
	s_nop 0
	v_pk_mul_f32 v[76:77], v[76:77], v[80:81]
	s_nop 0
	v_pk_mul_f32 v[72:73], v[72:73], v[76:77]
	v_pk_mul_f32 v[76:77], v[78:79], v[144:145] op_sel_hi:[1,0]
	s_nop 0
	v_mul_f32_e32 v78, 0xbfb8aa3b, v76
	v_mul_f32_e32 v79, 0xbfb8aa3b, v77
	v_exp_f32_e32 v78, v78
	v_exp_f32_e32 v79, v79
	v_add_f32_e32 v78, 1.0, v78
	v_add_f32_e32 v79, 1.0, v79
	v_rcp_f32_e32 v78, v78
	v_rcp_f32_e32 v79, v79
	s_nop 0
	v_pk_mul_f32 v[76:77], v[76:77], v[78:79]
	s_nop 0
	v_pk_mul_f32 v[74:75], v[74:75], v[76:77]
	v_mul_f32_e32 v76, 0xbfb8aa3b, v68
	v_mul_f32_e32 v77, 0xbfb8aa3b, v69
	v_exp_f32_e32 v76, v76
	v_exp_f32_e32 v77, v77
	v_add_f32_e32 v76, 1.0, v76
	v_add_f32_e32 v77, 1.0, v77
	v_rcp_f32_e32 v76, v76
	v_rcp_f32_e32 v77, v77
	s_nop 0
	v_pk_mul_f32 v[68:69], v[68:69], v[76:77]
	s_nop 0
	v_pk_mul_f32 v[68:69], v[64:65], v[68:69]
	v_pk_mul_f32 v[64:65], v[70:71], v[144:145] op_sel_hi:[1,0]
	s_nop 0
	v_mul_f32_e32 v70, 0xbfb8aa3b, v64
	v_mul_f32_e32 v71, 0xbfb8aa3b, v65
	v_exp_f32_e32 v70, v70
	v_exp_f32_e32 v71, v71
	v_add_f32_e32 v70, 1.0, v70
	v_add_f32_e32 v71, 1.0, v71
	v_rcp_f32_e32 v70, v70
	v_rcp_f32_e32 v71, v71
	s_nop 0
	v_pk_mul_f32 v[64:65], v[64:65], v[70:71]
	s_nop 0
	v_pk_mul_f32 v[70:71], v[66:67], v[64:65]
	v_cvt_pk_bf16_f32 v66, v68, v69
	v_mad_i64_i32 v[68:69], s[8:9], v172, s3, v[112:113]
	v_cvt_pk_bf16_f32 v64, v72, v73
	v_cvt_pk_bf16_f32 v65, v74, v75
	v_cvt_pk_bf16_f32 v67, v70, v71
	v_lshl_add_u64 v[68:69], v[68:69], 0, v[114:115]
	global_store_dwordx4 v[68:69], v[64:67], off
	s_nop 1
	v_mul_f32_e32 v64, 0xbfb8aa3b, v60
	v_mul_f32_e32 v65, 0xbfb8aa3b, v61
	v_exp_f32_e32 v64, v64
	v_exp_f32_e32 v65, v65
	v_add_f32_e32 v64, 1.0, v64
	v_add_f32_e32 v65, 1.0, v65
	v_rcp_f32_e32 v64, v64
	v_rcp_f32_e32 v65, v65
	s_nop 0
	v_pk_mul_f32 v[60:61], v[60:61], v[64:65]
	s_nop 0
	v_pk_mul_f32 v[56:57], v[56:57], v[60:61]
	v_pk_mul_f32 v[60:61], v[62:63], v[138:139] op_sel_hi:[1,0]
	s_nop 0
	v_mul_f32_e32 v62, 0xbfb8aa3b, v60
	v_mul_f32_e32 v63, 0xbfb8aa3b, v61
	v_exp_f32_e32 v62, v62
	v_exp_f32_e32 v63, v63
	v_add_f32_e32 v62, 1.0, v62
	v_add_f32_e32 v63, 1.0, v63
	v_rcp_f32_e32 v62, v62
	v_rcp_f32_e32 v63, v63
	s_nop 0
	v_pk_mul_f32 v[60:61], v[60:61], v[62:63]
	s_nop 0
	v_pk_mul_f32 v[58:59], v[58:59], v[60:61]
	v_mul_f32_e32 v60, 0xbfb8aa3b, v52
	v_mul_f32_e32 v61, 0xbfb8aa3b, v53
	v_exp_f32_e32 v60, v60
	v_exp_f32_e32 v61, v61
	v_add_f32_e32 v60, 1.0, v60
	v_add_f32_e32 v61, 1.0, v61
	v_rcp_f32_e32 v60, v60
	v_rcp_f32_e32 v61, v61
	s_nop 0
	v_pk_mul_f32 v[52:53], v[52:53], v[60:61]
	s_nop 0
	v_pk_mul_f32 v[52:53], v[48:49], v[52:53]
	v_pk_mul_f32 v[48:49], v[54:55], v[138:139] op_sel_hi:[1,0]
	s_nop 0
	v_mul_f32_e32 v54, 0xbfb8aa3b, v48
	v_mul_f32_e32 v55, 0xbfb8aa3b, v49
	v_exp_f32_e32 v54, v54
	v_exp_f32_e32 v55, v55
	v_add_f32_e32 v54, 1.0, v54
	v_add_f32_e32 v55, 1.0, v55
	v_rcp_f32_e32 v54, v54
	v_rcp_f32_e32 v55, v55
	s_nop 0
	v_pk_mul_f32 v[48:49], v[48:49], v[54:55]
	s_nop 0
	v_pk_mul_f32 v[54:55], v[50:51], v[48:49]
	v_cvt_pk_bf16_f32 v50, v52, v53
	v_mad_i64_i32 v[52:53], s[8:9], v170, s3, v[112:113]
	v_cvt_pk_bf16_f32 v48, v56, v57
	v_cvt_pk_bf16_f32 v49, v58, v59
	v_cvt_pk_bf16_f32 v51, v54, v55
	v_lshl_add_u64 v[52:53], v[52:53], 0, v[114:115]
	global_store_dwordx4 v[52:53], v[48:51], off
	s_nop 1
	v_mul_f32_e32 v48, 0xbfb8aa3b, v44
	v_mul_f32_e32 v49, 0xbfb8aa3b, v45
	v_exp_f32_e32 v48, v48
	v_exp_f32_e32 v49, v49
	v_add_f32_e32 v48, 1.0, v48
	v_add_f32_e32 v49, 1.0, v49
	v_rcp_f32_e32 v48, v48
	v_rcp_f32_e32 v49, v49
	s_nop 0
	v_pk_mul_f32 v[44:45], v[44:45], v[48:49]
	s_nop 0
	v_pk_mul_f32 v[40:41], v[40:41], v[44:45]
	v_pk_mul_f32 v[44:45], v[46:47], v[136:137] op_sel_hi:[1,0]
	s_nop 0
	v_mul_f32_e32 v46, 0xbfb8aa3b, v44
	v_mul_f32_e32 v47, 0xbfb8aa3b, v45
	v_exp_f32_e32 v46, v46
	v_exp_f32_e32 v47, v47
	v_add_f32_e32 v46, 1.0, v46
	v_add_f32_e32 v47, 1.0, v47
	v_rcp_f32_e32 v46, v46
	v_rcp_f32_e32 v47, v47
	s_nop 0
	v_pk_mul_f32 v[44:45], v[44:45], v[46:47]
	s_nop 0
	v_pk_mul_f32 v[42:43], v[42:43], v[44:45]
	v_mul_f32_e32 v44, 0xbfb8aa3b, v36
	v_mul_f32_e32 v45, 0xbfb8aa3b, v37
	v_exp_f32_e32 v44, v44
	v_exp_f32_e32 v45, v45
	v_add_f32_e32 v44, 1.0, v44
	v_add_f32_e32 v45, 1.0, v45
	v_rcp_f32_e32 v44, v44
	v_rcp_f32_e32 v45, v45
	s_nop 0
	v_pk_mul_f32 v[36:37], v[36:37], v[44:45]
	s_nop 0
	v_pk_mul_f32 v[36:37], v[32:33], v[36:37]
	v_pk_mul_f32 v[32:33], v[38:39], v[136:137] op_sel_hi:[1,0]
	s_nop 0
	v_mul_f32_e32 v38, 0xbfb8aa3b, v32
	v_mul_f32_e32 v39, 0xbfb8aa3b, v33
	v_exp_f32_e32 v38, v38
	v_exp_f32_e32 v39, v39
	v_add_f32_e32 v38, 1.0, v38
	v_add_f32_e32 v39, 1.0, v39
	v_rcp_f32_e32 v38, v38
	v_rcp_f32_e32 v39, v39
	s_nop 0
	v_pk_mul_f32 v[32:33], v[32:33], v[38:39]
	s_nop 0
	v_pk_mul_f32 v[38:39], v[34:35], v[32:33]
	v_cvt_pk_bf16_f32 v34, v36, v37
	v_mad_i64_i32 v[36:37], s[8:9], v168, s3, v[112:113]
	v_cvt_pk_bf16_f32 v32, v40, v41
	v_cvt_pk_bf16_f32 v33, v42, v43
	v_cvt_pk_bf16_f32 v35, v38, v39
	v_lshl_add_u64 v[36:37], v[36:37], 0, v[114:115]
	global_store_dwordx4 v[36:37], v[32:35], off
	s_nop 1
	v_mul_f32_e32 v32, 0xbfb8aa3b, v28
	v_mul_f32_e32 v33, 0xbfb8aa3b, v29
	v_exp_f32_e32 v32, v32
	v_exp_f32_e32 v33, v33
	v_add_f32_e32 v32, 1.0, v32
	v_add_f32_e32 v33, 1.0, v33
	v_rcp_f32_e32 v32, v32
	v_rcp_f32_e32 v33, v33
	s_nop 0
	v_pk_mul_f32 v[28:29], v[28:29], v[32:33]
	s_nop 0
	v_pk_mul_f32 v[24:25], v[24:25], v[28:29]
	v_pk_mul_f32 v[28:29], v[30:31], v[130:131] op_sel_hi:[1,0]
	s_nop 0
	v_mul_f32_e32 v30, 0xbfb8aa3b, v28
	v_mul_f32_e32 v31, 0xbfb8aa3b, v29
	v_exp_f32_e32 v30, v30
	v_exp_f32_e32 v31, v31
	v_add_f32_e32 v30, 1.0, v30
	v_add_f32_e32 v31, 1.0, v31
	v_rcp_f32_e32 v30, v30
	v_rcp_f32_e32 v31, v31
	s_nop 0
	v_pk_mul_f32 v[28:29], v[28:29], v[30:31]
	s_nop 0
	v_pk_mul_f32 v[26:27], v[26:27], v[28:29]
	v_mul_f32_e32 v28, 0xbfb8aa3b, v20
	v_mul_f32_e32 v29, 0xbfb8aa3b, v21
	v_exp_f32_e32 v28, v28
	v_exp_f32_e32 v29, v29
	v_add_f32_e32 v28, 1.0, v28
	v_add_f32_e32 v29, 1.0, v29
	v_rcp_f32_e32 v28, v28
	v_rcp_f32_e32 v29, v29
	s_nop 0
	v_pk_mul_f32 v[20:21], v[20:21], v[28:29]
	s_nop 0
	v_pk_mul_f32 v[20:21], v[16:17], v[20:21]
	v_pk_mul_f32 v[16:17], v[22:23], v[130:131] op_sel_hi:[1,0]
	s_nop 0
	v_mul_f32_e32 v22, 0xbfb8aa3b, v16
	v_mul_f32_e32 v23, 0xbfb8aa3b, v17
	v_exp_f32_e32 v22, v22
	v_exp_f32_e32 v23, v23
	v_add_f32_e32 v22, 1.0, v22
	v_add_f32_e32 v23, 1.0, v23
	v_rcp_f32_e32 v22, v22
	v_rcp_f32_e32 v23, v23
	s_nop 0
	v_pk_mul_f32 v[16:17], v[16:17], v[22:23]
	s_nop 0
	v_pk_mul_f32 v[22:23], v[18:19], v[16:17]
	v_cvt_pk_bf16_f32 v18, v20, v21
	v_mad_i64_i32 v[20:21], s[8:9], v166, s3, v[112:113]
	v_cvt_pk_bf16_f32 v16, v24, v25
	v_cvt_pk_bf16_f32 v17, v26, v27
	v_cvt_pk_bf16_f32 v19, v22, v23
	v_lshl_add_u64 v[20:21], v[20:21], 0, v[114:115]
	global_store_dwordx4 v[20:21], v[16:19], off
	s_nop 1
	v_mul_f32_e32 v16, 0xbfb8aa3b, v12
	v_mul_f32_e32 v17, 0xbfb8aa3b, v13
	v_exp_f32_e32 v16, v16
	v_exp_f32_e32 v17, v17
	v_add_f32_e32 v16, 1.0, v16
	v_add_f32_e32 v17, 1.0, v17
	v_rcp_f32_e32 v16, v16
	v_rcp_f32_e32 v17, v17
	s_nop 0
	v_pk_mul_f32 v[12:13], v[12:13], v[16:17]
	s_nop 0
	v_pk_mul_f32 v[8:9], v[8:9], v[12:13]
	v_pk_mul_f32 v[12:13], v[14:15], v[128:129] op_sel_hi:[1,0]
	s_nop 0
	v_mul_f32_e32 v14, 0xbfb8aa3b, v12
	v_mul_f32_e32 v15, 0xbfb8aa3b, v13
	v_exp_f32_e32 v14, v14
	v_exp_f32_e32 v15, v15
	v_add_f32_e32 v14, 1.0, v14
	v_add_f32_e32 v15, 1.0, v15
	v_rcp_f32_e32 v14, v14
	v_rcp_f32_e32 v15, v15
	s_nop 0
	v_pk_mul_f32 v[12:13], v[12:13], v[14:15]
	s_nop 0
	v_pk_mul_f32 v[10:11], v[10:11], v[12:13]
	v_mul_f32_e32 v12, 0xbfb8aa3b, v4
	v_mul_f32_e32 v13, 0xbfb8aa3b, v5
	v_exp_f32_e32 v12, v12
	v_exp_f32_e32 v13, v13
	v_add_f32_e32 v12, 1.0, v12
	v_add_f32_e32 v13, 1.0, v13
	v_rcp_f32_e32 v12, v12
	v_rcp_f32_e32 v13, v13
	s_nop 0
	v_pk_mul_f32 v[4:5], v[4:5], v[12:13]
	s_nop 0
	v_pk_mul_f32 v[4:5], v[0:1], v[4:5]
	v_pk_mul_f32 v[0:1], v[6:7], v[128:129] op_sel_hi:[1,0]
	s_nop 0
	v_mul_f32_e32 v6, 0xbfb8aa3b, v0
	v_mul_f32_e32 v7, 0xbfb8aa3b, v1
	v_exp_f32_e32 v6, v6
	v_exp_f32_e32 v7, v7
	v_add_f32_e32 v6, 1.0, v6
	v_add_f32_e32 v7, 1.0, v7
	v_rcp_f32_e32 v6, v6
	v_rcp_f32_e32 v7, v7
	s_nop 0
	v_pk_mul_f32 v[0:1], v[0:1], v[6:7]
	s_nop 0
	v_pk_mul_f32 v[6:7], v[2:3], v[0:1]
	v_cvt_pk_bf16_f32 v2, v4, v5
	v_mad_i64_i32 v[4:5], s[8:9], v164, s3, v[112:113]
	v_cvt_pk_bf16_f32 v0, v8, v9
	v_cvt_pk_bf16_f32 v1, v10, v11
	v_cvt_pk_bf16_f32 v3, v6, v7
	v_lshl_add_u64 v[4:5], v[4:5], 0, v[114:115]
	s_mov_b64 s[8:9], -1
	global_store_dwordx4 v[4:5], v[0:3], off
	s_cbranch_vccnz .LBB0_931
	s_andn2_b64 vcc, exec, s[10:11]
	s_cbranch_vccnz .LBB0_930
	s_barrier
	s_branch .LBB0_930

	.amdhsa_kernel _Z10hybrid_fwd4Args
		.amdhsa_group_segment_fixed_size 0
		.amdhsa_private_segment_fixed_size 0
		.amdhsa_kernarg_size 392
		.amdhsa_user_sgpr_count 2
		.amdhsa_user_sgpr_dispatch_ptr 0
		.amdhsa_user_sgpr_queue_ptr 0
		.amdhsa_user_sgpr_kernarg_segment_ptr 1
		.amdhsa_user_sgpr_dispatch_id 0
		.amdhsa_user_sgpr_kernarg_preload_length 0
		.amdhsa_user_sgpr_kernarg_preload_offset 0
		.amdhsa_user_sgpr_private_segment_size 0
		.amdhsa_uses_dynamic_stack 0
		.amdhsa_enable_private_segment 0
		.amdhsa_system_sgpr_workgroup_id_x 1
		.amdhsa_system_sgpr_workgroup_id_y 0
		.amdhsa_system_sgpr_workgroup_id_z 0
		.amdhsa_system_sgpr_workgroup_info 0
		.amdhsa_system_vgpr_workitem_id 2
		.amdhsa_next_free_vgpr 256
		.amdhsa_next_free_sgpr 102
		.amdhsa_accum_offset 256
		.amdhsa_reserve_vcc 1
		.amdhsa_float_round_mode_32 0
		.amdhsa_float_round_mode_16_64 0
		.amdhsa_float_denorm_mode_32 3
		.amdhsa_float_denorm_mode_16_64 3
		.amdhsa_dx10_clamp 1
		.amdhsa_ieee_mode 1
		.amdhsa_fp16_overflow 0
		.amdhsa_tg_split 0
		.amdhsa_exception_fp_ieee_invalid_op 0
		.amdhsa_exception_fp_denorm_src 0
		.amdhsa_exception_fp_ieee_div_zero 0
		.amdhsa_exception_fp_ieee_overflow 0
		.amdhsa_exception_fp_ieee_underflow 0
		.amdhsa_exception_fp_ieee_inexact 0
		.amdhsa_exception_int_div_zero 0
	.end_amdhsa_kernel

amdhsa.kernels:
  - .agpr_count:     0
    .args:
      - .offset:         0
        .size:           136
        .value_kind:     by_value
      - .offset:         136
        .size:           4
        .value_kind:     hidden_block_count_x
      - .offset:         140
        .size:           4
        .value_kind:     hidden_block_count_y
      - .offset:         144
        .size:           4
        .value_kind:     hidden_block_count_z
      - .offset:         148
        .size:           2
        .value_kind:     hidden_group_size_x
      - .offset:         150
        .size:           2
        .value_kind:     hidden_group_size_y
      - .offset:         152
        .size:           2
        .value_kind:     hidden_group_size_z
      - .offset:         154
        .size:           2
        .value_kind:     hidden_remainder_x
      - .offset:         156
        .size:           2
        .value_kind:     hidden_remainder_y
      - .offset:         158
        .size:           2
        .value_kind:     hidden_remainder_z
      - .offset:         176
        .size:           8
        .value_kind:     hidden_global_offset_x
      - .offset:         184
        .size:           8
        .value_kind:     hidden_global_offset_y
      - .offset:         192
        .size:           8
        .value_kind:     hidden_global_offset_z
      - .offset:         200
        .size:           2
        .value_kind:     hidden_grid_dims
      - .offset:         224
        .size:           8
        .value_kind:     hidden_multigrid_sync_arg
      - .offset:         256
        .size:           4
        .value_kind:     hidden_dynamic_lds_size
    .group_segment_fixed_size: 0
    .kernarg_segment_align: 8
    .kernarg_segment_size: 392
    .language:       OpenCL C
    .language_version:
      - 2
      - 0
    .max_flat_workgroup_size: 512
    .name:           _Z10hybrid_fwd4Args
    .private_segment_fixed_size: 0
    .sgpr_count:     108
    .sgpr_spill_count: 43
    .symbol:         _Z10hybrid_fwd4Args.kd
    .uniform_work_group_size: 1
    .uses_dynamic_stack: false
    .vgpr_count:     256
    .vgpr_spill_count: 0
    .wavefront_size: 64
